# grid barrier: non-leader workgroups poll the cross-XCD release word directly instead of the per-XCD one (one hop less)
# baseline (speedup 1.0000x reference)
.LBB0_548:
	s_or_b64 exec, exec, s[4:5]
	v_cvt_f32_u32_e32 v4, v2
	s_waitcnt vmcnt(0)
	v_readfirstlane_b32 s4, v3
	v_sub_u32_e32 v3, 0, v2
	v_rcp_iflag_f32_e32 v4, v4
	v_add_u32_e32 v5, s4, v1
	v_mul_f32_e32 v4, 0x4f7ffffe, v4
	v_cvt_u32_f32_e32 v4, v4
	v_mul_lo_u32 v1, v3, v4
	v_mul_hi_u32 v1, v4, v1
	v_add_u32_e32 v1, v4, v1
	v_mul_hi_u32 v1, v5, v1
	v_mul_lo_u32 v3, v1, v2
	v_sub_u32_e32 v3, v5, v3
	v_add_u32_e32 v4, 1, v1
	v_cmp_ge_u32_e32 vcc, v3, v2
	s_nop 1
	v_cndmask_b32_e32 v1, v1, v4, vcc
	v_sub_u32_e32 v4, v3, v2
	v_cndmask_b32_e32 v3, v3, v4, vcc
	v_add_u32_e32 v4, 1, v1
	v_cmp_ge_u32_e32 vcc, v3, v2
	v_add_u32_e32 v3, 1, v5
	s_nop 0
	v_cndmask_b32_e32 v1, v1, v4, vcc
	v_mul_lo_u32 v4, v2, v1
	v_add_u32_e32 v2, v4, v2
	v_cmp_ne_u32_e32 vcc, v3, v2
	s_and_saveexec_b64 s[4:5], vcc
	s_xor_b64 s[4:5], exec, s[4:5]
	s_cbranch_execz .LBB0_562
	v_readlane_b32 s6, v253, 21
	buffer_inv sc1
	v_readlane_b32 s7, v253, 22
	s_waitcnt lgkmcnt(0)
	s_nop 3
	global_load_dword v0, v65, s[6:7] sc1
	s_waitcnt vmcnt(0)
	v_cmp_eq_u32_e32 vcc, v0, v1
	s_and_saveexec_b64 s[6:7], vcc
	s_cbranch_execz .LBB0_561
	s_mov_b32 s27, 1
	s_mov_b64 s[30:31], 0
	s_branch .LBB0_552

.LBB0_554:
	v_readlane_b32 s28, v253, 21
	v_readlane_b32 s29, v253, 22
	s_add_i32 s27, s27, 1
	s_mov_b64 s[42:43], -1
	s_nop 2
	global_load_dword v0, v65, s[28:29] sc1
	s_waitcnt vmcnt(0)
	v_cmp_ne_u32_e32 vcc, v0, v1
	s_orn2_b64 s[38:39], vcc, exec
	s_branch .LBB0_551

.LBB0_1210:
	v_readlane_b32 s28, v253, 21
	v_readlane_b32 s29, v253, 22
	s_add_i32 s27, s27, 1
	s_mov_b64 s[44:45], -1
	s_nop 2
	global_load_dword v0, v65, s[28:29] sc1
	s_waitcnt vmcnt(0)
	v_cmp_ne_u32_e32 vcc, v0, v1
	s_orn2_b64 s[42:43], vcc, exec
	s_branch .LBB0_1207

.LBB0_1757:
	s_or_b64 exec, exec, s[4:5]
	v_cvt_f32_u32_e32 v4, v2
	s_waitcnt vmcnt(0)
	v_readfirstlane_b32 s4, v3
	v_sub_u32_e32 v3, 0, v2
	v_rcp_iflag_f32_e32 v4, v4
	v_add_u32_e32 v5, s4, v1
	v_mul_f32_e32 v4, 0x4f7ffffe, v4
	v_cvt_u32_f32_e32 v4, v4
	v_mul_lo_u32 v1, v3, v4
	v_mul_hi_u32 v1, v4, v1
	v_add_u32_e32 v1, v4, v1
	v_mul_hi_u32 v1, v5, v1
	v_mul_lo_u32 v3, v1, v2
	v_sub_u32_e32 v3, v5, v3
	v_add_u32_e32 v4, 1, v1
	v_cmp_ge_u32_e32 vcc, v3, v2
	s_nop 1
	v_cndmask_b32_e32 v1, v1, v4, vcc
	v_sub_u32_e32 v4, v3, v2
	v_cndmask_b32_e32 v3, v3, v4, vcc
	v_add_u32_e32 v4, 1, v1
	v_cmp_ge_u32_e32 vcc, v3, v2
	v_add_u32_e32 v3, 1, v5
	s_nop 0
	v_cndmask_b32_e32 v1, v1, v4, vcc
	v_mul_lo_u32 v4, v2, v1
	v_add_u32_e32 v2, v4, v2
	v_cmp_ne_u32_e32 vcc, v3, v2
	s_and_saveexec_b64 s[4:5], vcc
	s_xor_b64 s[4:5], exec, s[4:5]
	s_cbranch_execz .LBB0_1771
	v_readlane_b32 s6, v253, 21
	buffer_inv sc1
	v_readlane_b32 s7, v253, 22
	s_waitcnt lgkmcnt(0)
	s_nop 3
	global_load_dword v0, v65, s[6:7] sc1
	s_waitcnt vmcnt(0)
	v_cmp_eq_u32_e32 vcc, v0, v1
	s_and_saveexec_b64 s[6:7], vcc
	s_cbranch_execz .LBB0_1770
	s_mov_b32 s26, 1
	s_mov_b64 s[30:31], 0
	s_branch .LBB0_1761

.LBB0_1763:
	v_readlane_b32 s28, v253, 21
	v_readlane_b32 s29, v253, 22
	s_add_i32 s26, s26, 1
	s_mov_b64 s[42:43], -1
	s_nop 2
	global_load_dword v0, v65, s[28:29] sc1
	s_waitcnt vmcnt(0)
	v_cmp_ne_u32_e32 vcc, v0, v1
	s_orn2_b64 s[38:39], vcc, exec
	s_branch .LBB0_1760
